# P6 epilogue: W_out tiles staged without column permutation + lane transposition so each quad accesses 64 contiguous bytes; fgain hoisted
# speedup vs baseline: 1.0081x; 1.0047x over previous
.LBB0_522:
	s_cmp_lt_i32 s80, 7
	s_cselect_b64 s[0:1], -1, 0
	s_cmp_gt_i32 s81, 6
	s_cselect_b64 s[4:5], -1, 0
	s_and_b64 s[0:1], s[0:1], s[4:5]
	s_andn2_b64 vcc, exec, s[0:1]
	s_cbranch_vccnz .LBB0_622
	v_lshrrev_b32_e32 v2, 1, v144
	v_lshrrev_b32_e32 v3, 5, v144
	v_and_b32_e32 v2, 24, v2
	v_and_b32_e32 v3, 4, v3
	v_bfe_u32 v4, v144, 2, 2
	v_lshlrev_b32_e32 v0, 4, v144
	v_and_b32_e32 v1, 32, v144
	v_bfe_u32 v10, v144, 2, 4
	v_or3_b32 v2, v3, v4, v2
	v_lshrrev_b32_e32 v3, 3, v144
	s_movk_i32 s0, 0x70
	v_bitop3_b32 v8, v0, v1, 48 bitop3:0x6c
	v_and_b32_e32 v9, 64, v144
	v_and_or_b32 v4, v3, s0, v10
	s_movk_i32 s0, 0x60
	v_add_u32_e32 v11, 0x2000, v0
	v_or_b32_e32 v1, v8, v9
	v_and_or_b32 v3, v3, s0, v2
	v_lshrrev_b32_e32 v0, 7, v11
	s_movk_i32 s0, 0xf0
	s_add_u32 s30, s62, 0x4000000
	v_lshl_or_b32 v150, v4, 12, v1
	v_and_or_b32 v3, v0, s0, v10
	s_movk_i32 s0, 0xe0
	s_addc_u32 s31, s63, 0
	v_and_or_b32 v0, v0, s0, v2
	s_lshl_b32 s0, s2, 2
	s_and_b32 s0, s0, 28
	s_ashr_i32 s1, s2, 6
	s_add_i32 s0, s0, s1
	s_waitcnt lgkmcnt(0)
	s_bfe_u32 s16, s2, 0x30003
	s_ashr_i32 s1, s0, 31
	s_lshl_b64 s[6:7], s[0:1], 20
	s_lshl_b32 s2, s16, 20
	s_add_u32 s1, s62, s2
	s_addc_u32 s3, s63, 0
	s_add_u32 s4, s1, 0x1200000
	s_addc_u32 s5, s3, 0
	s_add_u32 s8, s1, 0x1280000
	s_addc_u32 s9, s3, 0
	s_add_u32 s6, s30, s6
	s_addc_u32 s7, s31, s7
	s_add_u32 s10, s6, 0x80000
	v_readfirstlane_b32 s3, v144
	s_addc_u32 s11, s7, 0
	s_lshr_b32 s18, s3, 6
	s_lshl_b32 s1, s18, 10
	s_add_i32 s34, s1, 0
	s_add_i32 m0, s34, 0x10000
	v_lshl_or_b32 v154, v3, 12, v1
	global_load_lds_dwordx4 v150, s[4:5]
	s_add_i32 m0, s34, 0x12000
	v_lshl_or_b32 v148, v4, 12, v1
	global_load_lds_dwordx4 v154, s[4:5]
	s_add_i32 m0, s34, 0x14000
	s_add_i32 s35, s34, 0x2000
	global_load_lds_dwordx4 v150, s[8:9]
	s_add_i32 m0, s34, 0x16000
	v_lshl_or_b32 v152, v3, 12, v1
	global_load_lds_dwordx4 v154, s[8:9]
	s_mov_b32 m0, s34
	s_add_i32 s36, s34, 0x4000
	global_load_lds_dwordx4 v148, s[6:7]
	s_mov_b32 m0, s35
	s_add_i32 s37, s34, 0x6000
	global_load_lds_dwordx4 v152, s[6:7]
	s_mov_b32 m0, s36
	v_mov_b32_e32 v151, 0
	global_load_lds_dwordx4 v148, s[10:11]
	s_mov_b32 m0, s37
	s_lshr_b32 s19, s3, 8
	global_load_lds_dwordx4 v152, s[10:11]
	v_mov_b32_e32 v155, v151
	v_mov_b32_e32 v149, v151
	v_mov_b32_e32 v153, v151
	s_cmp_eq_u32 s19, 1
	s_mov_b32 s38, 0
	v_lshl_add_u64 v[0:1], s[4:5], 0, v[150:151]
	v_lshl_add_u64 v[2:3], s[4:5], 0, v[154:155]
	v_lshl_add_u64 v[4:5], s[6:7], 0, v[148:149]
	s_cselect_b64 s[8:9], -1, 0
	s_cmp_lg_u32 s19, 1
	v_lshl_add_u64 v[6:7], s[6:7], 0, v[152:153]
	s_cbranch_scc1 .LBB0_525
	s_barrier

.LBB0_532:
	s_nop 7
	v_lshrrev_b32_e32 v224, 2, v193
	v_and_b32_e32 v225, 3, v193
	v_lshl_add_u32 v224, v225, 4, v224
	v_lshlrev_b32_e32 v224, 2, v224
	ds_bpermute_b32 v0, v224, v0
	ds_bpermute_b32 v1, v224, v1
	ds_bpermute_b32 v2, v224, v2
	ds_bpermute_b32 v3, v224, v3
	ds_bpermute_b32 v4, v224, v4
	ds_bpermute_b32 v5, v224, v5
	ds_bpermute_b32 v6, v224, v6
	ds_bpermute_b32 v7, v224, v7
	ds_bpermute_b32 v8, v224, v8
	ds_bpermute_b32 v9, v224, v9
	ds_bpermute_b32 v10, v224, v10
	ds_bpermute_b32 v11, v224, v11
	ds_bpermute_b32 v12, v224, v12
	ds_bpermute_b32 v13, v224, v13
	ds_bpermute_b32 v14, v224, v14
	ds_bpermute_b32 v15, v224, v15
	ds_bpermute_b32 v16, v224, v16
	ds_bpermute_b32 v17, v224, v17
	ds_bpermute_b32 v18, v224, v18
	ds_bpermute_b32 v19, v224, v19
	ds_bpermute_b32 v20, v224, v20
	ds_bpermute_b32 v21, v224, v21
	ds_bpermute_b32 v22, v224, v22
	ds_bpermute_b32 v23, v224, v23
	ds_bpermute_b32 v24, v224, v24
	ds_bpermute_b32 v25, v224, v25
	ds_bpermute_b32 v26, v224, v26
	ds_bpermute_b32 v27, v224, v27
	ds_bpermute_b32 v28, v224, v28
	ds_bpermute_b32 v29, v224, v29
	ds_bpermute_b32 v30, v224, v30
	ds_bpermute_b32 v31, v224, v31
	ds_bpermute_b32 v32, v224, v32
	ds_bpermute_b32 v33, v224, v33
	ds_bpermute_b32 v34, v224, v34
	ds_bpermute_b32 v35, v224, v35
	ds_bpermute_b32 v36, v224, v36
	ds_bpermute_b32 v37, v224, v37
	ds_bpermute_b32 v38, v224, v38
	ds_bpermute_b32 v39, v224, v39
	ds_bpermute_b32 v40, v224, v40
	ds_bpermute_b32 v41, v224, v41
	ds_bpermute_b32 v42, v224, v42
	ds_bpermute_b32 v43, v224, v43
	ds_bpermute_b32 v44, v224, v44
	ds_bpermute_b32 v45, v224, v45
	ds_bpermute_b32 v46, v224, v46
	ds_bpermute_b32 v47, v224, v47
	ds_bpermute_b32 v48, v224, v48
	ds_bpermute_b32 v49, v224, v49
	ds_bpermute_b32 v50, v224, v50
	ds_bpermute_b32 v51, v224, v51
	ds_bpermute_b32 v52, v224, v52
	ds_bpermute_b32 v53, v224, v53
	ds_bpermute_b32 v54, v224, v54
	ds_bpermute_b32 v55, v224, v55
	ds_bpermute_b32 v56, v224, v56
	ds_bpermute_b32 v57, v224, v57
	ds_bpermute_b32 v58, v224, v58
	ds_bpermute_b32 v59, v224, v59
	ds_bpermute_b32 v60, v224, v60
	ds_bpermute_b32 v61, v224, v61
	ds_bpermute_b32 v62, v224, v62
	ds_bpermute_b32 v63, v224, v63
	ds_bpermute_b32 v64, v224, v64
	ds_bpermute_b32 v65, v224, v65
	ds_bpermute_b32 v66, v224, v66
	ds_bpermute_b32 v67, v224, v67
	ds_bpermute_b32 v68, v224, v68
	ds_bpermute_b32 v69, v224, v69
	ds_bpermute_b32 v70, v224, v70
	ds_bpermute_b32 v71, v224, v71
	ds_bpermute_b32 v72, v224, v72
	ds_bpermute_b32 v73, v224, v73
	ds_bpermute_b32 v74, v224, v74
	ds_bpermute_b32 v75, v224, v75
	ds_bpermute_b32 v76, v224, v76
	ds_bpermute_b32 v77, v224, v77
	ds_bpermute_b32 v78, v224, v78
	ds_bpermute_b32 v79, v224, v79
	ds_bpermute_b32 v80, v224, v80
	ds_bpermute_b32 v81, v224, v81
	ds_bpermute_b32 v82, v224, v82
	ds_bpermute_b32 v83, v224, v83
	ds_bpermute_b32 v84, v224, v84
	ds_bpermute_b32 v85, v224, v85
	ds_bpermute_b32 v86, v224, v86
	ds_bpermute_b32 v87, v224, v87
	ds_bpermute_b32 v88, v224, v88
	ds_bpermute_b32 v89, v224, v89
	ds_bpermute_b32 v90, v224, v90
	ds_bpermute_b32 v91, v224, v91
	ds_bpermute_b32 v92, v224, v92
	ds_bpermute_b32 v93, v224, v93
	ds_bpermute_b32 v94, v224, v94
	ds_bpermute_b32 v95, v224, v95
	ds_bpermute_b32 v112, v224, v112
	ds_bpermute_b32 v113, v224, v113
	ds_bpermute_b32 v114, v224, v114
	ds_bpermute_b32 v115, v224, v115
	ds_bpermute_b32 v116, v224, v116
	ds_bpermute_b32 v117, v224, v117
	ds_bpermute_b32 v118, v224, v118
	ds_bpermute_b32 v119, v224, v119
	ds_bpermute_b32 v120, v224, v120
	ds_bpermute_b32 v121, v224, v121
	ds_bpermute_b32 v122, v224, v122
	ds_bpermute_b32 v123, v224, v123
	ds_bpermute_b32 v124, v224, v124
	ds_bpermute_b32 v125, v224, v125
	ds_bpermute_b32 v126, v224, v126
	ds_bpermute_b32 v127, v224, v127
	ds_bpermute_b32 v128, v224, v128
	ds_bpermute_b32 v129, v224, v129
	ds_bpermute_b32 v130, v224, v130
	ds_bpermute_b32 v131, v224, v131
	ds_bpermute_b32 v132, v224, v132
	ds_bpermute_b32 v133, v224, v133
	ds_bpermute_b32 v134, v224, v134
	ds_bpermute_b32 v135, v224, v135
	ds_bpermute_b32 v136, v224, v136
	ds_bpermute_b32 v137, v224, v137
	ds_bpermute_b32 v138, v224, v138
	ds_bpermute_b32 v139, v224, v139
	ds_bpermute_b32 v140, v224, v140
	ds_bpermute_b32 v141, v224, v141
	ds_bpermute_b32 v142, v224, v142
	ds_bpermute_b32 v143, v224, v143
	s_waitcnt lgkmcnt(0)
	v_and_b32_e32 v175, 3, v193
	v_lshrrev_b32_e32 v96, 2, v193
	v_mov_b32_e32 v185, v193
	s_lshl_b32 s26, s67, 8
	v_add_u32_e32 v184, s49, v96
	v_add_u32_e32 v158, s26, v184
	v_ashrrev_i32_e32 v159, 31, v158
	v_lshl_add_u64 v[96:97], v[158:159], 2, s[10:11]
	v_add_co_u32_e32 v98, vcc, s50, v96
	s_ashr_i32 s2, s67, 31
	s_nop 0
	v_addc_co_u32_e32 v99, vcc, 0, v97, vcc
	v_add_co_u32_e32 v100, vcc, s56, v96
	s_lshr_b32 s2, s2, 26
	s_nop 0
	v_addc_co_u32_e32 v101, vcc, 0, v97, vcc
	global_load_dword v174, v[96:97], off
	global_load_dword v186, v[98:99], off
	global_load_dword v187, v[100:101], off
	s_add_i32 s2, s67, s2
	s_lshl_b32 s2, s2, 5
	s_and_b32 s2, s2, 0xfffff800
	s_ashr_i32 s3, s2, 31
	v_lshl_add_u32 v168, v175, 2, s53
	s_lshl_b64 s[2:3], s[2:3], 2
	s_add_u32 s2, s39, s2
	v_ashrrev_i32_e32 v169, 31, v168
	v_lshlrev_b64 v[96:97], 13, v[158:159]
	s_addc_u32 s3, s40, s3
	v_lshlrev_b64 v[156:157], 2, v[168:169]
	v_lshl_add_u64 v[96:97], s[64:65], 0, v[96:97]
	v_lshl_add_u64 v[108:109], s[2:3], 0, v[156:157]
	v_lshl_add_u64 v[110:111], v[96:97], 0, v[156:157]
	global_load_dwordx4 v[160:163], v[110:111], off nt
	global_load_dwordx4 v[104:107], v[108:109], off
	global_load_dwordx4 v[100:103], v[108:109], off offset:64
	global_load_dwordx4 v[164:167], v[110:111], off offset:64 nt
	global_load_dwordx4 v[96:99], v[108:109], off offset:512
	global_load_dwordx4 v[170:173], v[110:111], off offset:512 nt
	global_load_dwordx4 v[188:191], v[110:111], off offset:576 nt
	s_nop 0
	global_load_dwordx4 v[108:111], v[108:109], off offset:576
	v_and_b32_e32 v194, 64, v182
	v_add_u32_e32 v202, 64, v194
	v_xor_b32_e32 v192, 1, v182
	v_cmp_lt_i32_e32 vcc, v192, v202
	v_cmp_eq_u32_e64 s[2:3], 0, v175
	s_waitcnt vmcnt(0)
	v_add_f32_e32 v174, v174, v186
	v_add_f32_e32 v174, v174, v187
	v_fmamk_f32 v174, v174, 0x3a2aaaab, v183
	v_rsq_f32_e32 v174, v174
	v_cndmask_b32_e32 v186, v182, v192, vcc
	v_lshlrev_b32_e32 v186, 2, v186
	v_pk_mul_f32 v[194:195], v[140:141], v[174:175] op_sel_hi:[1,0]
	v_pk_mul_f32 v[140:141], v[142:143], v[174:175] op_sel_hi:[1,0]
	v_pk_mul_f32 v[196:197], v[136:137], v[174:175] op_sel_hi:[1,0]
	v_pk_mul_f32 v[136:137], v[138:139], v[174:175] op_sel_hi:[1,0]
	v_pk_mul_f32 v[198:199], v[132:133], v[174:175] op_sel_hi:[1,0]
	v_pk_mul_f32 v[132:133], v[134:135], v[174:175] op_sel_hi:[1,0]
	v_pk_fma_f32 v[140:141], v[106:107], v[140:141], v[162:163]
	v_pk_fma_f32 v[142:143], v[104:105], v[194:195], v[160:161]
	v_pk_fma_f32 v[136:137], v[102:103], v[136:137], v[166:167]
	v_pk_fma_f32 v[138:139], v[100:101], v[196:197], v[164:165]
	v_pk_mul_f32 v[200:201], v[128:129], v[174:175] op_sel_hi:[1,0]
	v_pk_mul_f32 v[128:129], v[130:131], v[174:175] op_sel_hi:[1,0]
	v_pk_fma_f32 v[132:133], v[98:99], v[132:133], v[172:173]
	v_pk_fma_f32 v[134:135], v[96:97], v[198:199], v[170:171]
	v_mul_f32_e32 v160, v143, v143
	v_mul_f32_e32 v161, v141, v141
	v_mul_f32_e32 v162, v139, v139
	v_mul_f32_e32 v163, v137, v137
	v_pk_fma_f32 v[128:129], v[110:111], v[128:129], v[190:191]
	v_pk_fma_f32 v[130:131], v[108:109], v[200:201], v[188:189]
	v_mul_f32_e32 v164, v135, v135
	v_mul_f32_e32 v165, v133, v133
	v_fmac_f32_e32 v160, v142, v142
	v_fmac_f32_e32 v161, v140, v140
	v_fmac_f32_e32 v162, v138, v138
	v_fmac_f32_e32 v163, v136, v136
	v_mul_f32_e32 v166, v131, v131
	v_mul_f32_e32 v167, v129, v129
	v_fmac_f32_e32 v164, v134, v134
	v_fmac_f32_e32 v165, v132, v132
	v_add_f32_e32 v160, v160, v161
	v_add_f32_e32 v161, v162, v163
	v_fmac_f32_e32 v166, v130, v130
	v_fmac_f32_e32 v167, v128, v128
	v_add_f32_e32 v162, v164, v165
	v_add_f32_e32 v160, v160, v161
	v_add_f32_e32 v160, v162, v160
	v_add_f32_e32 v161, v166, v167
	v_add_f32_e32 v160, v161, v160
	ds_bpermute_b32 v161, v186, v160
	v_xor_b32_e32 v162, 2, v182
	v_cmp_lt_i32_e32 vcc, v162, v202
	s_waitcnt lgkmcnt(0)
	v_add_f32_e32 v160, v160, v161
	v_cndmask_b32_e32 v162, v182, v162, vcc
	v_lshlrev_b32_e32 v187, 2, v162
	ds_bpermute_b32 v161, v187, v160
	s_and_saveexec_b64 s[24:25], s[2:3]
	s_cbranch_execz .LBB0_534
	v_lshl_add_u32 v162, v184, 4, s51
	s_waitcnt lgkmcnt(0)
	v_add_f32_e32 v160, v160, v161
	ds_write_b32 v162, v160
.LBB0_534:
	s_or_b64 exec, exec, s[24:25]
	v_add_u32_e32 v164, 16, v184
	v_add_u32_e32 v160, s26, v164
	s_waitcnt lgkmcnt(0)
	v_ashrrev_i32_e32 v161, 31, v160
	v_lshl_add_u64 v[162:163], v[160:161], 2, s[10:11]
	v_add_co_u32_e32 v166, vcc, 0x20000, v162
	s_nop 1
	v_addc_co_u32_e32 v167, vcc, 0, v163, vcc
	v_add_co_u32_e32 v170, vcc, 0x40000, v162
	s_nop 1
	v_addc_co_u32_e32 v171, vcc, 0, v163, vcc
	global_load_dword v165, v[162:163], off
	s_nop 0
	global_load_dword v166, v[166:167], off
	s_nop 0
	global_load_dword v167, v[170:171], off
	v_lshlrev_b64 v[162:163], 13, v[160:161]
	v_lshl_add_u64 v[162:163], s[64:65], 0, v[162:163]
	v_lshl_add_u64 v[162:163], v[168:169], 2, v[162:163]
	global_load_dwordx4 v[170:173], v[162:163], off nt
	global_load_dwordx4 v[188:191], v[162:163], off offset:64 nt
	global_load_dwordx4 v[194:197], v[162:163], off offset:512 nt
	global_load_dwordx4 v[198:201], v[162:163], off offset:576 nt
	s_waitcnt vmcnt(5)
	v_add_f32_e32 v162, v165, v166
	s_waitcnt vmcnt(4)
	v_add_f32_e32 v162, v162, v167
	v_fmamk_f32 v162, v162, 0x3a2aaaab, v183
	v_rsq_f32_e32 v162, v162
	s_nop 0
	v_pk_mul_f32 v[124:125], v[124:125], v[162:163] op_sel_hi:[1,0]
	v_pk_mul_f32 v[126:127], v[126:127], v[162:163] op_sel_hi:[1,0]
	v_pk_mul_f32 v[120:121], v[120:121], v[162:163] op_sel_hi:[1,0]
	v_pk_mul_f32 v[122:123], v[122:123], v[162:163] op_sel_hi:[1,0]
	v_pk_mul_f32 v[166:167], v[116:117], v[162:163] op_sel_hi:[1,0]
	v_pk_mul_f32 v[116:117], v[118:119], v[162:163] op_sel_hi:[1,0]
	v_pk_mul_f32 v[174:175], v[112:113], v[162:163] op_sel_hi:[1,0]
	v_pk_mul_f32 v[112:113], v[114:115], v[162:163] op_sel_hi:[1,0]
	s_waitcnt vmcnt(3)
	v_pk_fma_f32 v[126:127], v[106:107], v[126:127], v[172:173]
	v_pk_fma_f32 v[162:163], v[104:105], v[124:125], v[170:171]
	s_waitcnt vmcnt(2)
	v_pk_fma_f32 v[122:123], v[102:103], v[122:123], v[190:191]
	v_pk_fma_f32 v[124:125], v[100:101], v[120:121], v[188:189]
	s_waitcnt vmcnt(1)
	v_pk_fma_f32 v[116:117], v[98:99], v[116:117], v[196:197]
	v_pk_fma_f32 v[118:119], v[96:97], v[166:167], v[194:195]
	v_mul_f32_e32 v120, v163, v163
	v_mul_f32_e32 v121, v127, v127
	v_mul_f32_e32 v165, v125, v125
	v_mul_f32_e32 v166, v123, v123
	s_waitcnt vmcnt(0)
	v_pk_fma_f32 v[112:113], v[110:111], v[112:113], v[200:201]
	v_pk_fma_f32 v[114:115], v[108:109], v[174:175], v[198:199]
	v_mul_f32_e32 v167, v119, v119
	v_mul_f32_e32 v170, v117, v117
	v_fmac_f32_e32 v120, v162, v162
	v_fmac_f32_e32 v121, v126, v126
	v_fmac_f32_e32 v165, v124, v124
	v_fmac_f32_e32 v166, v122, v122
	v_mul_f32_e32 v171, v115, v115
	v_mul_f32_e32 v172, v113, v113
	v_fmac_f32_e32 v167, v118, v118
	v_fmac_f32_e32 v170, v116, v116
	v_add_f32_e32 v120, v120, v121
	v_add_f32_e32 v121, v165, v166
	v_fmac_f32_e32 v171, v114, v114
	v_fmac_f32_e32 v172, v112, v112
	v_add_f32_e32 v165, v167, v170
	v_add_f32_e32 v120, v120, v121
	v_add_f32_e32 v120, v165, v120
	v_add_f32_e32 v121, v171, v172
	v_add_f32_e32 v120, v121, v120
	ds_bpermute_b32 v121, v186, v120
	s_waitcnt lgkmcnt(0)
	v_add_f32_e32 v120, v120, v121
	ds_bpermute_b32 v121, v187, v120
	s_and_saveexec_b64 s[24:25], s[2:3]
	s_cbranch_execz .LBB0_536
	v_lshl_add_u32 v164, v164, 4, s51
	s_waitcnt lgkmcnt(0)
	v_add_f32_e32 v120, v120, v121
	ds_write_b32 v164, v120
.LBB0_536:
	s_or_b64 exec, exec, s[24:25]
	v_add_u32_e32 v166, 32, v184
	v_add_u32_e32 v120, s26, v166
	s_waitcnt lgkmcnt(0)
	v_ashrrev_i32_e32 v121, 31, v120
	v_lshl_add_u64 v[164:165], v[120:121], 2, s[10:11]
	v_add_co_u32_e32 v170, vcc, 0x20000, v164
	s_nop 1
	v_addc_co_u32_e32 v171, vcc, 0, v165, vcc
	v_add_co_u32_e32 v172, vcc, 0x40000, v164
	s_nop 1
	v_addc_co_u32_e32 v173, vcc, 0, v165, vcc
	global_load_dword v167, v[164:165], off
	global_load_dword v174, v[170:171], off
	global_load_dword v175, v[172:173], off
	v_lshlrev_b64 v[164:165], 13, v[120:121]
	v_lshl_add_u64 v[164:165], s[64:65], 0, v[164:165]
	v_lshl_add_u64 v[164:165], v[168:169], 2, v[164:165]
	global_load_dwordx4 v[170:173], v[164:165], off nt
	global_load_dwordx4 v[188:191], v[164:165], off offset:64 nt
	global_load_dwordx4 v[194:197], v[164:165], off offset:512 nt
	global_load_dwordx4 v[198:201], v[164:165], off offset:576 nt
	s_waitcnt vmcnt(5)
	v_add_f32_e32 v164, v167, v174
	s_waitcnt vmcnt(4)
	v_add_f32_e32 v164, v164, v175
	v_fmamk_f32 v164, v164, 0x3a2aaaab, v183
	v_rsq_f32_e32 v164, v164
	s_nop 0
	v_pk_mul_f32 v[92:93], v[92:93], v[164:165] op_sel_hi:[1,0]
	v_pk_mul_f32 v[94:95], v[94:95], v[164:165] op_sel_hi:[1,0]
	v_pk_mul_f32 v[174:175], v[88:89], v[164:165] op_sel_hi:[1,0]
	v_pk_mul_f32 v[88:89], v[90:91], v[164:165] op_sel_hi:[1,0]
	v_pk_mul_f32 v[202:203], v[84:85], v[164:165] op_sel_hi:[1,0]
	v_pk_mul_f32 v[84:85], v[86:87], v[164:165] op_sel_hi:[1,0]
	v_pk_mul_f32 v[204:205], v[80:81], v[164:165] op_sel_hi:[1,0]
	v_pk_mul_f32 v[80:81], v[82:83], v[164:165] op_sel_hi:[1,0]
	s_waitcnt vmcnt(3)
	v_pk_fma_f32 v[94:95], v[106:107], v[94:95], v[172:173]
	v_pk_fma_f32 v[164:165], v[104:105], v[92:93], v[170:171]
	s_waitcnt vmcnt(2)
	v_pk_fma_f32 v[88:89], v[102:103], v[88:89], v[190:191]
	v_pk_fma_f32 v[90:91], v[100:101], v[174:175], v[188:189]
	s_waitcnt vmcnt(1)
	v_pk_fma_f32 v[84:85], v[98:99], v[84:85], v[196:197]
	v_pk_fma_f32 v[86:87], v[96:97], v[202:203], v[194:195]
	v_mul_f32_e32 v92, v165, v165
	v_mul_f32_e32 v93, v95, v95
	v_mul_f32_e32 v167, v91, v91
	v_mul_f32_e32 v170, v89, v89
	s_waitcnt vmcnt(0)
	v_pk_fma_f32 v[80:81], v[110:111], v[80:81], v[200:201]
	v_pk_fma_f32 v[82:83], v[108:109], v[204:205], v[198:199]
	v_mul_f32_e32 v171, v87, v87
	v_mul_f32_e32 v172, v85, v85
	v_fmac_f32_e32 v92, v164, v164
	v_fmac_f32_e32 v93, v94, v94
	v_fmac_f32_e32 v167, v90, v90
	v_fmac_f32_e32 v170, v88, v88
	v_mul_f32_e32 v173, v83, v83
	v_mul_f32_e32 v174, v81, v81
	v_fmac_f32_e32 v171, v86, v86
	v_fmac_f32_e32 v172, v84, v84
	v_add_f32_e32 v92, v92, v93
	v_add_f32_e32 v93, v167, v170
	v_fmac_f32_e32 v173, v82, v82
	v_fmac_f32_e32 v174, v80, v80
	v_add_f32_e32 v167, v171, v172
	v_add_f32_e32 v92, v92, v93
	v_add_f32_e32 v92, v167, v92
	v_add_f32_e32 v93, v173, v174
	v_add_f32_e32 v92, v93, v92
	ds_bpermute_b32 v93, v186, v92
	s_waitcnt lgkmcnt(0)
	v_add_f32_e32 v92, v92, v93
	ds_bpermute_b32 v93, v187, v92
	s_and_saveexec_b64 s[24:25], s[2:3]
	s_cbranch_execz .LBB0_538
	v_lshl_add_u32 v166, v166, 4, s51
	s_waitcnt lgkmcnt(0)
	v_add_f32_e32 v92, v92, v93
	ds_write_b32 v166, v92
.LBB0_538:
	s_or_b64 exec, exec, s[24:25]
	v_add_u32_e32 v170, 48, v184
	v_add_u32_e32 v92, s26, v170
	s_waitcnt lgkmcnt(0)
	v_ashrrev_i32_e32 v93, 31, v92
	v_lshl_add_u64 v[166:167], v[92:93], 2, s[10:11]
	v_add_co_u32_e32 v172, vcc, 0x20000, v166
	s_nop 1
	v_addc_co_u32_e32 v173, vcc, 0, v167, vcc
	v_add_co_u32_e32 v174, vcc, 0x40000, v166
	s_nop 1
	v_addc_co_u32_e32 v175, vcc, 0, v167, vcc
	global_load_dword v171, v[166:167], off
	global_load_dword v192, v[172:173], off
	global_load_dword v202, v[174:175], off
	v_lshlrev_b64 v[166:167], 13, v[92:93]
	v_lshl_add_u64 v[166:167], s[64:65], 0, v[166:167]
	v_lshl_add_u64 v[166:167], v[168:169], 2, v[166:167]
	global_load_dwordx4 v[172:175], v[166:167], off nt
	global_load_dwordx4 v[188:191], v[166:167], off offset:64 nt
	global_load_dwordx4 v[194:197], v[166:167], off offset:512 nt
	global_load_dwordx4 v[198:201], v[166:167], off offset:576 nt
	s_waitcnt vmcnt(5)
	v_add_f32_e32 v166, v171, v192
	s_waitcnt vmcnt(4)
	v_add_f32_e32 v166, v166, v202
	v_fmamk_f32 v166, v166, 0x3a2aaaab, v183
	v_rsq_f32_e32 v166, v166
	s_nop 0
	v_pk_mul_f32 v[76:77], v[76:77], v[166:167] op_sel_hi:[1,0]
	v_pk_mul_f32 v[78:79], v[78:79], v[166:167] op_sel_hi:[1,0]
	v_pk_mul_f32 v[72:73], v[72:73], v[166:167] op_sel_hi:[1,0]
	v_pk_mul_f32 v[74:75], v[74:75], v[166:167] op_sel_hi:[1,0]
	v_pk_mul_f32 v[202:203], v[68:69], v[166:167] op_sel_hi:[1,0]
	v_pk_mul_f32 v[68:69], v[70:71], v[166:167] op_sel_hi:[1,0]
	v_pk_mul_f32 v[204:205], v[64:65], v[166:167] op_sel_hi:[1,0]
	v_pk_mul_f32 v[64:65], v[66:67], v[166:167] op_sel_hi:[1,0]
	s_waitcnt vmcnt(3)
	v_pk_fma_f32 v[78:79], v[106:107], v[78:79], v[174:175]
	v_pk_fma_f32 v[166:167], v[104:105], v[76:77], v[172:173]
	s_waitcnt vmcnt(2)
	v_pk_fma_f32 v[74:75], v[102:103], v[74:75], v[190:191]
	v_pk_fma_f32 v[76:77], v[100:101], v[72:73], v[188:189]
	s_waitcnt vmcnt(1)
	v_pk_fma_f32 v[68:69], v[98:99], v[68:69], v[196:197]
	v_pk_fma_f32 v[70:71], v[96:97], v[202:203], v[194:195]
	v_mul_f32_e32 v72, v167, v167
	v_mul_f32_e32 v73, v79, v79
	v_mul_f32_e32 v171, v77, v77
	v_mul_f32_e32 v172, v75, v75
	s_waitcnt vmcnt(0)
	v_pk_fma_f32 v[64:65], v[110:111], v[64:65], v[200:201]
	v_pk_fma_f32 v[66:67], v[108:109], v[204:205], v[198:199]
	v_mul_f32_e32 v173, v71, v71
	v_mul_f32_e32 v174, v69, v69
	v_fmac_f32_e32 v72, v166, v166
	v_fmac_f32_e32 v73, v78, v78
	v_fmac_f32_e32 v171, v76, v76
	v_fmac_f32_e32 v172, v74, v74
	v_mul_f32_e32 v175, v67, v67
	v_mul_f32_e32 v188, v65, v65
	v_fmac_f32_e32 v173, v70, v70
	v_fmac_f32_e32 v174, v68, v68
	v_add_f32_e32 v72, v72, v73
	v_add_f32_e32 v73, v171, v172
	v_fmac_f32_e32 v175, v66, v66
	v_fmac_f32_e32 v188, v64, v64
	v_add_f32_e32 v171, v173, v174
	v_add_f32_e32 v72, v72, v73
	v_add_f32_e32 v72, v171, v72
	v_add_f32_e32 v73, v175, v188
	v_add_f32_e32 v72, v73, v72
	ds_bpermute_b32 v73, v186, v72
	s_waitcnt lgkmcnt(0)
	v_add_f32_e32 v72, v72, v73
	ds_bpermute_b32 v73, v187, v72
	s_and_saveexec_b64 s[24:25], s[2:3]
	s_cbranch_execz .LBB0_540
	v_lshl_add_u32 v170, v170, 4, s51
	s_waitcnt lgkmcnt(0)
	v_add_f32_e32 v72, v72, v73
	ds_write_b32 v170, v72
.LBB0_540:
	s_or_b64 exec, exec, s[24:25]
	v_add_u32_e32 v172, 0x80, v184
	v_add_u32_e32 v72, s26, v172
	s_waitcnt lgkmcnt(0)
	v_ashrrev_i32_e32 v73, 31, v72
	v_lshl_add_u64 v[170:171], v[72:73], 2, s[10:11]
	v_add_co_u32_e32 v174, vcc, 0x20000, v170
	s_nop 1
	v_addc_co_u32_e32 v175, vcc, 0, v171, vcc
	v_add_co_u32_e32 v188, vcc, 0x40000, v170
	s_nop 1
	v_addc_co_u32_e32 v189, vcc, 0, v171, vcc
	global_load_dword v173, v[170:171], off
	s_nop 0
	global_load_dword v174, v[174:175], off
	s_nop 0
	global_load_dword v175, v[188:189], off
	v_lshlrev_b64 v[170:171], 13, v[72:73]
	v_lshl_add_u64 v[170:171], s[64:65], 0, v[170:171]
	v_lshl_add_u64 v[170:171], v[168:169], 2, v[170:171]
	global_load_dwordx4 v[188:191], v[170:171], off nt
	global_load_dwordx4 v[194:197], v[170:171], off offset:64 nt
	global_load_dwordx4 v[198:201], v[170:171], off offset:512 nt
	global_load_dwordx4 v[202:205], v[170:171], off offset:576 nt
	s_waitcnt vmcnt(5)
	v_add_f32_e32 v170, v173, v174
	s_waitcnt vmcnt(4)
	v_add_f32_e32 v170, v170, v175
	v_fmamk_f32 v170, v170, 0x3a2aaaab, v183
	v_rsq_f32_e32 v170, v170
	s_nop 0
	v_pk_mul_f32 v[60:61], v[60:61], v[170:171] op_sel_hi:[1,0]
	v_pk_mul_f32 v[62:63], v[62:63], v[170:171] op_sel_hi:[1,0]
	v_pk_mul_f32 v[174:175], v[56:57], v[170:171] op_sel_hi:[1,0]
	v_pk_mul_f32 v[56:57], v[58:59], v[170:171] op_sel_hi:[1,0]
	v_pk_mul_f32 v[206:207], v[52:53], v[170:171] op_sel_hi:[1,0]
	v_pk_mul_f32 v[52:53], v[54:55], v[170:171] op_sel_hi:[1,0]
	v_pk_mul_f32 v[208:209], v[48:49], v[170:171] op_sel_hi:[1,0]
	v_pk_mul_f32 v[48:49], v[50:51], v[170:171] op_sel_hi:[1,0]
	s_waitcnt vmcnt(3)
	v_pk_fma_f32 v[62:63], v[106:107], v[62:63], v[190:191]
	v_pk_fma_f32 v[170:171], v[104:105], v[60:61], v[188:189]
	s_waitcnt vmcnt(2)
	v_pk_fma_f32 v[56:57], v[102:103], v[56:57], v[196:197]
	v_pk_fma_f32 v[58:59], v[100:101], v[174:175], v[194:195]
	s_waitcnt vmcnt(1)
	v_pk_fma_f32 v[52:53], v[98:99], v[52:53], v[200:201]
	v_pk_fma_f32 v[54:55], v[96:97], v[206:207], v[198:199]
	v_mul_f32_e32 v60, v171, v171
	v_mul_f32_e32 v61, v63, v63
	v_mul_f32_e32 v173, v59, v59
	v_mul_f32_e32 v174, v57, v57
	s_waitcnt vmcnt(0)
	v_pk_fma_f32 v[48:49], v[110:111], v[48:49], v[204:205]
	v_pk_fma_f32 v[50:51], v[108:109], v[208:209], v[202:203]
	v_mul_f32_e32 v175, v55, v55
	v_mul_f32_e32 v188, v53, v53
	v_fmac_f32_e32 v60, v170, v170
	v_fmac_f32_e32 v61, v62, v62
	v_fmac_f32_e32 v173, v58, v58
	v_fmac_f32_e32 v174, v56, v56
	v_mul_f32_e32 v189, v51, v51
	v_mul_f32_e32 v190, v49, v49
	v_fmac_f32_e32 v175, v54, v54
	v_fmac_f32_e32 v188, v52, v52
	v_add_f32_e32 v60, v60, v61
	v_add_f32_e32 v61, v173, v174
	v_fmac_f32_e32 v189, v50, v50
	v_fmac_f32_e32 v190, v48, v48
	v_add_f32_e32 v173, v175, v188
	v_add_f32_e32 v60, v60, v61
	v_add_f32_e32 v60, v173, v60
	v_add_f32_e32 v61, v189, v190
	v_add_f32_e32 v60, v61, v60
	ds_bpermute_b32 v61, v186, v60
	s_waitcnt lgkmcnt(0)
	v_add_f32_e32 v60, v60, v61
	ds_bpermute_b32 v61, v187, v60
	s_and_saveexec_b64 s[24:25], s[2:3]
	s_cbranch_execz .LBB0_542
	v_lshl_add_u32 v172, v172, 4, s51
	s_waitcnt lgkmcnt(0)
	v_add_f32_e32 v60, v60, v61
	ds_write_b32 v172, v60
.LBB0_542:
	s_or_b64 exec, exec, s[24:25]
	v_add_u32_e32 v174, 0x90, v184
	v_add_u32_e32 v60, s26, v174
	s_waitcnt lgkmcnt(0)
	v_ashrrev_i32_e32 v61, 31, v60
	v_lshl_add_u64 v[172:173], v[60:61], 2, s[10:11]
	v_add_co_u32_e32 v188, vcc, 0x20000, v172
	s_nop 1
	v_addc_co_u32_e32 v189, vcc, 0, v173, vcc
	v_add_co_u32_e32 v190, vcc, 0x40000, v172
	s_nop 1
	v_addc_co_u32_e32 v191, vcc, 0, v173, vcc
	global_load_dword v175, v[172:173], off
	global_load_dword v192, v[188:189], off
	global_load_dword v206, v[190:191], off
	v_lshlrev_b64 v[172:173], 13, v[60:61]
	v_lshl_add_u64 v[172:173], s[64:65], 0, v[172:173]
	v_lshl_add_u64 v[172:173], v[168:169], 2, v[172:173]
	global_load_dwordx4 v[188:191], v[172:173], off nt
	global_load_dwordx4 v[194:197], v[172:173], off offset:64 nt
	global_load_dwordx4 v[198:201], v[172:173], off offset:512 nt
	global_load_dwordx4 v[202:205], v[172:173], off offset:576 nt
	s_waitcnt vmcnt(5)
	v_add_f32_e32 v172, v175, v192
	s_waitcnt vmcnt(4)
	v_add_f32_e32 v172, v172, v206
	v_fmamk_f32 v172, v172, 0x3a2aaaab, v183
	v_rsq_f32_e32 v172, v172
	s_nop 0
	v_pk_mul_f32 v[44:45], v[44:45], v[172:173] op_sel_hi:[1,0]
	v_pk_mul_f32 v[46:47], v[46:47], v[172:173] op_sel_hi:[1,0]
	v_pk_mul_f32 v[40:41], v[40:41], v[172:173] op_sel_hi:[1,0]
	v_pk_mul_f32 v[42:43], v[42:43], v[172:173] op_sel_hi:[1,0]
	v_pk_mul_f32 v[206:207], v[36:37], v[172:173] op_sel_hi:[1,0]
	v_pk_mul_f32 v[36:37], v[38:39], v[172:173] op_sel_hi:[1,0]
	v_pk_mul_f32 v[208:209], v[32:33], v[172:173] op_sel_hi:[1,0]
	v_pk_mul_f32 v[32:33], v[34:35], v[172:173] op_sel_hi:[1,0]
	s_waitcnt vmcnt(3)
	v_pk_fma_f32 v[46:47], v[106:107], v[46:47], v[190:191]
	v_pk_fma_f32 v[172:173], v[104:105], v[44:45], v[188:189]
	s_waitcnt vmcnt(2)
	v_pk_fma_f32 v[42:43], v[102:103], v[42:43], v[196:197]
	v_pk_fma_f32 v[44:45], v[100:101], v[40:41], v[194:195]
	s_waitcnt vmcnt(1)
	v_pk_fma_f32 v[36:37], v[98:99], v[36:37], v[200:201]
	v_pk_fma_f32 v[38:39], v[96:97], v[206:207], v[198:199]
	v_mul_f32_e32 v40, v173, v173
	v_mul_f32_e32 v41, v47, v47
	v_mul_f32_e32 v175, v45, v45
	v_mul_f32_e32 v188, v43, v43
	s_waitcnt vmcnt(0)
	v_pk_fma_f32 v[32:33], v[110:111], v[32:33], v[204:205]
	v_pk_fma_f32 v[34:35], v[108:109], v[208:209], v[202:203]
	v_mul_f32_e32 v189, v39, v39
	v_mul_f32_e32 v190, v37, v37
	v_fmac_f32_e32 v40, v172, v172
	v_fmac_f32_e32 v41, v46, v46
	v_fmac_f32_e32 v175, v44, v44
	v_fmac_f32_e32 v188, v42, v42
	v_mul_f32_e32 v191, v35, v35
	v_mul_f32_e32 v192, v33, v33
	v_fmac_f32_e32 v189, v38, v38
	v_fmac_f32_e32 v190, v36, v36
	v_add_f32_e32 v40, v40, v41
	v_add_f32_e32 v41, v175, v188
	v_fmac_f32_e32 v191, v34, v34
	v_fmac_f32_e32 v192, v32, v32
	v_add_f32_e32 v175, v189, v190
	v_add_f32_e32 v40, v40, v41
	v_add_f32_e32 v40, v175, v40
	v_add_f32_e32 v41, v191, v192
	v_add_f32_e32 v40, v41, v40
	ds_bpermute_b32 v41, v186, v40
	s_waitcnt lgkmcnt(0)
	v_add_f32_e32 v40, v40, v41
	ds_bpermute_b32 v41, v187, v40
	s_and_saveexec_b64 s[24:25], s[2:3]
	s_cbranch_execz .LBB0_544
	v_lshl_add_u32 v174, v174, 4, s51
	s_waitcnt lgkmcnt(0)
	v_add_f32_e32 v40, v40, v41
	ds_write_b32 v174, v40
.LBB0_544:
	s_or_b64 exec, exec, s[24:25]
	v_add_u32_e32 v188, 0xa0, v184
	v_add_u32_e32 v40, s26, v188
	s_waitcnt lgkmcnt(0)
	v_ashrrev_i32_e32 v41, 31, v40
	v_lshl_add_u64 v[174:175], v[40:41], 2, s[10:11]
	v_add_co_u32_e32 v190, vcc, 0x20000, v174
	s_nop 1
	v_addc_co_u32_e32 v191, vcc, 0, v175, vcc
	v_add_co_u32_e32 v194, vcc, 0x40000, v174
	s_nop 1
	v_addc_co_u32_e32 v195, vcc, 0, v175, vcc
	global_load_dword v189, v[174:175], off
	s_nop 0
	global_load_dword v190, v[190:191], off
	s_nop 0
	global_load_dword v191, v[194:195], off
	v_lshlrev_b64 v[174:175], 13, v[40:41]
	v_lshl_add_u64 v[174:175], s[64:65], 0, v[174:175]
	v_lshl_add_u64 v[174:175], v[168:169], 2, v[174:175]
	global_load_dwordx4 v[194:197], v[174:175], off nt
	global_load_dwordx4 v[198:201], v[174:175], off offset:64 nt
	global_load_dwordx4 v[202:205], v[174:175], off offset:512 nt
	global_load_dwordx4 v[206:209], v[174:175], off offset:576 nt
	s_waitcnt vmcnt(5)
	v_add_f32_e32 v174, v189, v190
	s_waitcnt vmcnt(4)
	v_add_f32_e32 v174, v174, v191
	v_fmamk_f32 v174, v174, 0x3a2aaaab, v183
	v_rsq_f32_e32 v174, v174
	s_nop 0
	v_pk_mul_f32 v[28:29], v[28:29], v[174:175] op_sel_hi:[1,0]
	v_pk_mul_f32 v[30:31], v[30:31], v[174:175] op_sel_hi:[1,0]
	v_pk_mul_f32 v[190:191], v[24:25], v[174:175] op_sel_hi:[1,0]
	v_pk_mul_f32 v[24:25], v[26:27], v[174:175] op_sel_hi:[1,0]
	v_pk_mul_f32 v[210:211], v[20:21], v[174:175] op_sel_hi:[1,0]
	v_pk_mul_f32 v[20:21], v[22:23], v[174:175] op_sel_hi:[1,0]
	v_pk_mul_f32 v[212:213], v[16:17], v[174:175] op_sel_hi:[1,0]
	v_pk_mul_f32 v[16:17], v[18:19], v[174:175] op_sel_hi:[1,0]
	s_waitcnt vmcnt(3)
	v_pk_fma_f32 v[30:31], v[106:107], v[30:31], v[196:197]
	v_pk_fma_f32 v[174:175], v[104:105], v[28:29], v[194:195]
	s_waitcnt vmcnt(2)
	v_pk_fma_f32 v[24:25], v[102:103], v[24:25], v[200:201]
	v_pk_fma_f32 v[26:27], v[100:101], v[190:191], v[198:199]
	s_waitcnt vmcnt(1)
	v_pk_fma_f32 v[20:21], v[98:99], v[20:21], v[204:205]
	v_pk_fma_f32 v[22:23], v[96:97], v[210:211], v[202:203]
	v_mul_f32_e32 v28, v175, v175
	v_mul_f32_e32 v29, v31, v31
	v_mul_f32_e32 v189, v27, v27
	v_mul_f32_e32 v190, v25, v25
	s_waitcnt vmcnt(0)
	v_pk_fma_f32 v[16:17], v[110:111], v[16:17], v[208:209]
	v_pk_fma_f32 v[18:19], v[108:109], v[212:213], v[206:207]
	v_mul_f32_e32 v191, v23, v23
	v_mul_f32_e32 v192, v21, v21
	v_fmac_f32_e32 v28, v174, v174
	v_fmac_f32_e32 v29, v30, v30
	v_fmac_f32_e32 v189, v26, v26
	v_fmac_f32_e32 v190, v24, v24
	v_mul_f32_e32 v194, v19, v19
	v_mul_f32_e32 v195, v17, v17
	v_fmac_f32_e32 v191, v22, v22
	v_fmac_f32_e32 v192, v20, v20
	v_add_f32_e32 v28, v28, v29
	v_add_f32_e32 v29, v189, v190
	v_fmac_f32_e32 v194, v18, v18
	v_fmac_f32_e32 v195, v16, v16
	v_add_f32_e32 v189, v191, v192
	v_add_f32_e32 v28, v28, v29
	v_add_f32_e32 v28, v189, v28
	v_add_f32_e32 v29, v194, v195
	v_add_f32_e32 v28, v29, v28
	ds_bpermute_b32 v29, v186, v28
	s_waitcnt lgkmcnt(0)
	v_add_f32_e32 v28, v28, v29
	ds_bpermute_b32 v29, v187, v28
	s_and_saveexec_b64 s[24:25], s[2:3]
	s_cbranch_execz .LBB0_546
	v_lshl_add_u32 v188, v188, 4, s51
	s_waitcnt lgkmcnt(0)
	v_add_f32_e32 v28, v28, v29
	ds_write_b32 v188, v28
.LBB0_546:
	s_or_b64 exec, exec, s[24:25]
	v_add_u32_e32 v188, 0xb0, v184
	v_add_u32_e32 v28, s26, v188
	s_waitcnt lgkmcnt(0)
	v_ashrrev_i32_e32 v29, 31, v28
	v_lshl_add_u64 v[190:191], v[28:29], 2, s[10:11]
	v_add_co_u32_e32 v194, vcc, 0x20000, v190
	s_nop 1
	v_addc_co_u32_e32 v195, vcc, 0, v191, vcc
	v_add_co_u32_e32 v196, vcc, 0x40000, v190
	s_nop 1
	v_addc_co_u32_e32 v197, vcc, 0, v191, vcc
	global_load_dword v189, v[190:191], off
	global_load_dword v192, v[194:195], off
	global_load_dword v210, v[196:197], off
	v_lshlrev_b64 v[190:191], 13, v[28:29]
	v_lshl_add_u64 v[190:191], s[64:65], 0, v[190:191]
	v_lshl_add_u64 v[168:169], v[168:169], 2, v[190:191]
	global_load_dwordx4 v[194:197], v[168:169], off nt
	global_load_dwordx4 v[198:201], v[168:169], off offset:64 nt
	global_load_dwordx4 v[202:205], v[168:169], off offset:512 nt
	global_load_dwordx4 v[206:209], v[168:169], off offset:576 nt
	s_waitcnt vmcnt(5)
	v_add_f32_e32 v168, v189, v192
	s_waitcnt vmcnt(4)
	v_add_f32_e32 v168, v168, v210
	v_fmamk_f32 v168, v168, 0x3a2aaaab, v183
	v_rsq_f32_e32 v168, v168
	s_nop 0
	v_pk_mul_f32 v[190:191], v[12:13], v[168:169] op_sel_hi:[1,0]
	v_pk_mul_f32 v[12:13], v[14:15], v[168:169] op_sel_hi:[1,0]
	v_pk_mul_f32 v[210:211], v[8:9], v[168:169] op_sel_hi:[1,0]
	v_pk_mul_f32 v[8:9], v[10:11], v[168:169] op_sel_hi:[1,0]
	v_pk_mul_f32 v[212:213], v[4:5], v[168:169] op_sel_hi:[1,0]
	v_pk_mul_f32 v[4:5], v[6:7], v[168:169] op_sel_hi:[1,0]
	s_waitcnt vmcnt(3)
	v_pk_fma_f32 v[12:13], v[106:107], v[12:13], v[196:197]
	v_pk_fma_f32 v[14:15], v[104:105], v[190:191], v[194:195]
	s_waitcnt vmcnt(2)
	v_pk_fma_f32 v[8:9], v[102:103], v[8:9], v[200:201]
	v_pk_fma_f32 v[10:11], v[100:101], v[210:211], v[198:199]
	v_pk_mul_f32 v[214:215], v[0:1], v[168:169] op_sel_hi:[1,0]
	v_pk_mul_f32 v[0:1], v[2:3], v[168:169] op_sel_hi:[1,0]
	s_waitcnt vmcnt(1)
	v_pk_fma_f32 v[4:5], v[98:99], v[4:5], v[204:205]
	v_pk_fma_f32 v[6:7], v[96:97], v[212:213], v[202:203]
	v_mul_f32_e32 v96, v15, v15
	v_mul_f32_e32 v97, v13, v13
	v_mul_f32_e32 v98, v11, v11
	v_mul_f32_e32 v99, v9, v9
	s_waitcnt vmcnt(0)
	v_pk_fma_f32 v[0:1], v[110:111], v[0:1], v[208:209]
	v_pk_fma_f32 v[2:3], v[108:109], v[214:215], v[206:207]
	v_mul_f32_e32 v100, v7, v7
	v_mul_f32_e32 v101, v5, v5
	v_fmac_f32_e32 v96, v14, v14
	v_fmac_f32_e32 v97, v12, v12
	v_fmac_f32_e32 v98, v10, v10
	v_fmac_f32_e32 v99, v8, v8
	v_mul_f32_e32 v102, v3, v3
	v_mul_f32_e32 v103, v1, v1
	v_fmac_f32_e32 v100, v6, v6
	v_fmac_f32_e32 v101, v4, v4
	v_add_f32_e32 v96, v96, v97
	v_add_f32_e32 v97, v98, v99
	v_fmac_f32_e32 v102, v2, v2
	v_fmac_f32_e32 v103, v0, v0
	v_add_f32_e32 v98, v100, v101
	v_add_f32_e32 v96, v96, v97
	v_add_f32_e32 v96, v98, v96
	v_add_f32_e32 v97, v102, v103
	v_add_f32_e32 v96, v97, v96
	ds_bpermute_b32 v97, v186, v96
	s_waitcnt lgkmcnt(0)
	v_add_f32_e32 v96, v96, v97
	ds_bpermute_b32 v97, v187, v96
	s_and_saveexec_b64 s[24:25], s[2:3]
	s_cbranch_execz .LBB0_548
	v_lshl_add_u32 v98, v188, 4, s51
	s_waitcnt lgkmcnt(0)
	v_add_f32_e32 v96, v96, v97
	ds_write_b32 v98, v96
.LBB0_548:
	s_or_b64 exec, exec, s[24:25]
	v_lshl_add_u64 v[240:241], s[58:59], 0, v[156:157]
	global_load_dwordx4 v[224:227], v[240:241], off
	global_load_dwordx4 v[228:231], v[240:241], off offset:64
	global_load_dwordx4 v[232:235], v[240:241], off offset:512
	global_load_dwordx4 v[236:239], v[240:241], off offset:576
	s_waitcnt lgkmcnt(0)
	s_barrier
	v_add_u32_e32 v98, s52, v185
	v_cndmask_b32_e64 v96, 0, 1, s[18:19]
	v_cmp_ne_u32_e64 s[2:3], 1, v96
	v_add_u32_e32 v96, s26, v98
	s_andn2_b64 vcc, exec, s[18:19]
	s_waitcnt lgkmcnt(0)
	v_ashrrev_i32_e32 v97, 31, v96
	s_cbranch_vccnz .LBB0_553
	v_lshl_add_u32 v99, v98, 4, 0
	v_add_u32_e32 v99, 0x20000, v99
	ds_read_b128 v[100:103], v99
	v_lshlrev_b64 v[104:105], 5, v[96:97]
	v_cmp_eq_u32_e32 vcc, 0, v185
	s_waitcnt lgkmcnt(0)
	v_mov_b32_e32 v106, v101
	v_mov_b32_e32 v107, v102
	v_mov_b32_e32 v101, v103
	v_pk_add_f32 v[100:101], v[106:107], v[100:101]
	v_lshl_add_u64 v[102:103], s[16:17], 0, v[104:105]
	v_pk_add_f32 v[100:101], v[100:101], v[100:101] op_sel:[0,1] op_sel_hi:[1,0]
	global_store_dword v[102:103], v100, off sc1
	s_waitcnt vmcnt(0)
	s_and_saveexec_b64 s[24:25], vcc
	s_cbranch_execz .LBB0_552
	s_mov_b64 s[26:27], exec
	v_mbcnt_lo_u32_b32 v99, s26, 0
	v_mbcnt_hi_u32_b32 v99, s27, v99
	v_cmp_eq_u32_e32 vcc, 0, v99
	s_and_b64 s[28:29], exec, vcc
	s_mov_b64 exec, s[28:29]
	s_cbranch_execz .LBB0_552
	s_lshl_b32 s28, s67, 6
	s_ashr_i32 s29, s28, 31
	s_lshl_b64 s[28:29], s[28:29], 2
	s_add_u32 s28, s41, s28
	s_addc_u32 s29, s42, s29
	s_bcnt1_i32_b64 s26, s[26:27]
	v_mov_b32_e32 v99, s26
	global_atomic_add v151, v99, s[28:29]

.LBB0_565:
	s_waitcnt lgkmcnt(0)
	s_barrier
	v_lshl_add_u32 v102, v184, 2, 0
	v_add_u32_e32 v110, 0x21000, v102
	ds_read2_b32 v[102:103], v110 offset1:16
	v_lshlrev_b64 v[104:105], 11, v[158:159]
	v_lshl_add_u64 v[104:105], v[104:105], 2, s[60:61]
	v_lshl_add_u64 v[104:105], v[104:105], 0, v[156:157]
	s_cmp_eq_u32 s66, 3
	s_waitcnt lgkmcnt(0)
	v_pk_mul_f32 v[106:107], v[142:143], v[102:103] op_sel_hi:[1,0]
	v_pk_mul_f32 v[108:109], v[140:141], v[102:103] op_sel_hi:[1,0]
	s_mov_b64 s[2:3], -1
	v_pk_mul_f32 v[100:101], v[226:227], v[108:109]
	v_pk_mul_f32 v[98:99], v[224:225], v[106:107]
	global_store_dwordx4 v[104:105], v[98:101], off
	v_pk_mul_f32 v[106:107], v[138:139], v[102:103] op_sel_hi:[1,0]
	v_pk_mul_f32 v[108:109], v[136:137], v[102:103] op_sel_hi:[1,0]
	v_pk_mul_f32 v[98:99], v[106:107], v[228:229]
	v_pk_mul_f32 v[100:101], v[108:109], v[230:231]
	global_store_dwordx4 v[104:105], v[98:101], off offset:64
	v_pk_mul_f32 v[106:107], v[134:135], v[102:103] op_sel_hi:[1,0]
	v_pk_mul_f32 v[108:109], v[132:133], v[102:103] op_sel_hi:[1,0]
	v_pk_mul_f32 v[98:99], v[106:107], v[232:233]
	v_pk_mul_f32 v[100:101], v[108:109], v[234:235]
	global_store_dwordx4 v[104:105], v[98:101], off offset:512
	v_pk_mul_f32 v[106:107], v[130:131], v[102:103] op_sel_hi:[1,0]
	v_pk_mul_f32 v[108:109], v[128:129], v[102:103] op_sel_hi:[1,0]
	v_mov_b32_e32 v102, v103
	v_pk_mul_f32 v[100:101], v[108:109], v[238:239]
	v_pk_mul_f32 v[98:99], v[106:107], v[236:237]
	global_store_dwordx4 v[104:105], v[98:101], off offset:576
	v_lshlrev_b64 v[104:105], 11, v[160:161]
	v_lshl_add_u64 v[104:105], v[104:105], 2, s[60:61]
	v_pk_mul_f32 v[106:107], v[162:163], v[102:103] op_sel_hi:[1,0]
	v_pk_mul_f32 v[108:109], v[126:127], v[102:103] op_sel_hi:[1,0]
	v_lshl_add_u64 v[104:105], v[104:105], 0, v[156:157]
	v_pk_mul_f32 v[100:101], v[226:227], v[108:109]
	v_pk_mul_f32 v[98:99], v[224:225], v[106:107]
	global_store_dwordx4 v[104:105], v[98:101], off
	v_pk_mul_f32 v[106:107], v[124:125], v[102:103] op_sel_hi:[1,0]
	v_pk_mul_f32 v[108:109], v[122:123], v[102:103] op_sel_hi:[1,0]
	v_pk_mul_f32 v[98:99], v[106:107], v[228:229]
	v_pk_mul_f32 v[100:101], v[108:109], v[230:231]
	global_store_dwordx4 v[104:105], v[98:101], off offset:64
	v_pk_mul_f32 v[106:107], v[118:119], v[102:103] op_sel_hi:[1,0]
	v_pk_mul_f32 v[108:109], v[116:117], v[102:103] op_sel_hi:[1,0]
	v_pk_mul_f32 v[98:99], v[106:107], v[232:233]
	v_pk_mul_f32 v[100:101], v[108:109], v[234:235]
	global_store_dwordx4 v[104:105], v[98:101], off offset:512
	v_pk_mul_f32 v[106:107], v[114:115], v[102:103] op_sel_hi:[1,0]
	v_pk_mul_f32 v[102:103], v[112:113], v[102:103] op_sel_hi:[1,0]
	v_pk_mul_f32 v[98:99], v[106:107], v[236:237]
	v_pk_mul_f32 v[100:101], v[102:103], v[238:239]
	global_store_dwordx4 v[104:105], v[98:101], off offset:576
	ds_read2_b32 v[102:103], v110 offset0:32 offset1:48
	v_lshlrev_b64 v[104:105], 11, v[120:121]
	v_lshl_add_u64 v[104:105], v[104:105], 2, s[60:61]
	v_lshl_add_u64 v[104:105], v[104:105], 0, v[156:157]
	s_waitcnt lgkmcnt(0)
	v_pk_mul_f32 v[106:107], v[164:165], v[102:103] op_sel_hi:[1,0]
	v_pk_mul_f32 v[94:95], v[94:95], v[102:103] op_sel_hi:[1,0]
	v_pk_mul_f32 v[88:89], v[88:89], v[102:103] op_sel_hi:[1,0]
	v_pk_mul_f32 v[84:85], v[84:85], v[102:103] op_sel_hi:[1,0]
	v_pk_mul_f32 v[80:81], v[80:81], v[102:103] op_sel_hi:[1,0]
	v_pk_mul_f32 v[100:101], v[226:227], v[94:95]
	v_pk_mul_f32 v[98:99], v[224:225], v[106:107]
	global_store_dwordx4 v[104:105], v[98:101], off
	v_pk_mul_f32 v[94:95], v[90:91], v[102:103] op_sel_hi:[1,0]
	v_pk_mul_f32 v[90:91], v[88:89], v[230:231]
	v_pk_mul_f32 v[88:89], v[94:95], v[228:229]
	global_store_dwordx4 v[104:105], v[88:91], off offset:64
	v_pk_mul_f32 v[94:95], v[86:87], v[102:103] op_sel_hi:[1,0]
	v_pk_mul_f32 v[86:87], v[84:85], v[234:235]
	v_pk_mul_f32 v[84:85], v[94:95], v[232:233]
	global_store_dwordx4 v[104:105], v[84:87], off offset:512
	v_pk_mul_f32 v[88:89], v[82:83], v[102:103] op_sel_hi:[1,0]
	v_pk_mul_f32 v[82:83], v[80:81], v[238:239]
	v_pk_mul_f32 v[80:81], v[88:89], v[236:237]
	global_store_dwordx4 v[104:105], v[80:83], off offset:576
	v_lshlrev_b64 v[84:85], 11, v[92:93]
	v_mov_b32_e32 v86, v103
	v_lshl_add_u64 v[84:85], v[84:85], 2, s[60:61]
	v_pk_mul_f32 v[88:89], v[166:167], v[86:87] op_sel_hi:[1,0]
	v_pk_mul_f32 v[78:79], v[78:79], v[86:87] op_sel_hi:[1,0]
	v_lshl_add_u64 v[84:85], v[84:85], 0, v[156:157]
	v_pk_mul_f32 v[74:75], v[74:75], v[86:87] op_sel_hi:[1,0]
	v_pk_mul_f32 v[68:69], v[68:69], v[86:87] op_sel_hi:[1,0]
	v_pk_mul_f32 v[64:65], v[64:65], v[86:87] op_sel_hi:[1,0]
	v_pk_mul_f32 v[82:83], v[226:227], v[78:79]
	v_pk_mul_f32 v[80:81], v[224:225], v[88:89]
	global_store_dwordx4 v[84:85], v[80:83], off
	s_nop 1
	s_nop 0
	v_pk_mul_f32 v[82:83], v[76:77], v[86:87] op_sel_hi:[1,0]
	v_pk_mul_f32 v[76:77], v[74:75], v[230:231]
	v_pk_mul_f32 v[74:75], v[82:83], v[228:229]
	global_store_dwordx4 v[84:85], v[74:77], off offset:64
	v_pk_mul_f32 v[78:79], v[70:71], v[86:87] op_sel_hi:[1,0]
	v_pk_mul_f32 v[70:71], v[68:69], v[234:235]
	v_pk_mul_f32 v[68:69], v[78:79], v[232:233]
	global_store_dwordx4 v[84:85], v[68:71], off offset:512
	v_pk_mul_f32 v[74:75], v[66:67], v[86:87] op_sel_hi:[1,0]
	v_pk_mul_f32 v[66:67], v[64:65], v[238:239]
	v_pk_mul_f32 v[64:65], v[74:75], v[236:237]
	global_store_dwordx4 v[84:85], v[64:67], off offset:576
	ds_read2_b32 v[68:69], v110 offset0:128 offset1:144
	v_lshlrev_b64 v[70:71], 11, v[72:73]
	v_lshl_add_u64 v[70:71], v[70:71], 2, s[60:61]
	v_lshl_add_u64 v[70:71], v[70:71], 0, v[156:157]
	s_waitcnt lgkmcnt(0)
	v_pk_mul_f32 v[72:73], v[170:171], v[68:69] op_sel_hi:[1,0]
	v_pk_mul_f32 v[62:63], v[62:63], v[68:69] op_sel_hi:[1,0]
	v_pk_mul_f32 v[56:57], v[56:57], v[68:69] op_sel_hi:[1,0]
	v_pk_mul_f32 v[52:53], v[52:53], v[68:69] op_sel_hi:[1,0]
	v_pk_mul_f32 v[48:49], v[48:49], v[68:69] op_sel_hi:[1,0]
	v_pk_mul_f32 v[66:67], v[226:227], v[62:63]
	v_pk_mul_f32 v[64:65], v[224:225], v[72:73]
	global_store_dwordx4 v[70:71], v[64:67], off
	s_nop 1
	s_nop 0
	v_pk_mul_f32 v[66:67], v[58:59], v[68:69] op_sel_hi:[1,0]
	v_pk_mul_f32 v[58:59], v[56:57], v[230:231]
	v_pk_mul_f32 v[56:57], v[66:67], v[228:229]
	global_store_dwordx4 v[70:71], v[56:59], off offset:64
	v_pk_mul_f32 v[62:63], v[54:55], v[68:69] op_sel_hi:[1,0]
	v_pk_mul_f32 v[54:55], v[52:53], v[234:235]
	v_pk_mul_f32 v[52:53], v[62:63], v[232:233]
	global_store_dwordx4 v[70:71], v[52:55], off offset:512
	v_pk_mul_f32 v[56:57], v[50:51], v[68:69] op_sel_hi:[1,0]
	v_pk_mul_f32 v[50:51], v[48:49], v[238:239]
	v_pk_mul_f32 v[48:49], v[56:57], v[236:237]
	global_store_dwordx4 v[70:71], v[48:51], off offset:576
	v_lshlrev_b64 v[52:53], 11, v[60:61]
	v_mov_b32_e32 v54, v69
	v_lshl_add_u64 v[52:53], v[52:53], 2, s[60:61]
	v_pk_mul_f32 v[56:57], v[172:173], v[54:55] op_sel_hi:[1,0]
	v_pk_mul_f32 v[46:47], v[46:47], v[54:55] op_sel_hi:[1,0]
	v_lshl_add_u64 v[52:53], v[52:53], 0, v[156:157]
	v_pk_mul_f32 v[42:43], v[42:43], v[54:55] op_sel_hi:[1,0]
	v_pk_mul_f32 v[36:37], v[36:37], v[54:55] op_sel_hi:[1,0]
	v_pk_mul_f32 v[32:33], v[32:33], v[54:55] op_sel_hi:[1,0]
	v_pk_mul_f32 v[50:51], v[226:227], v[46:47]
	v_pk_mul_f32 v[48:49], v[224:225], v[56:57]
	global_store_dwordx4 v[52:53], v[48:51], off
	s_nop 1
	s_nop 0
	v_pk_mul_f32 v[50:51], v[44:45], v[54:55] op_sel_hi:[1,0]
	v_pk_mul_f32 v[44:45], v[42:43], v[230:231]
	v_pk_mul_f32 v[42:43], v[50:51], v[228:229]
	global_store_dwordx4 v[52:53], v[42:45], off offset:64
	v_pk_mul_f32 v[46:47], v[38:39], v[54:55] op_sel_hi:[1,0]
	v_pk_mul_f32 v[38:39], v[36:37], v[234:235]
	v_pk_mul_f32 v[36:37], v[46:47], v[232:233]
	global_store_dwordx4 v[52:53], v[36:39], off offset:512
	v_pk_mul_f32 v[42:43], v[34:35], v[54:55] op_sel_hi:[1,0]
	v_pk_mul_f32 v[34:35], v[32:33], v[238:239]
	v_pk_mul_f32 v[32:33], v[42:43], v[236:237]
	global_store_dwordx4 v[52:53], v[32:35], off offset:576
	ds_read2_b32 v[36:37], v110 offset0:160 offset1:176
	v_lshlrev_b64 v[38:39], 11, v[40:41]
	v_lshl_add_u64 v[38:39], v[38:39], 2, s[60:61]
	v_lshl_add_u64 v[38:39], v[38:39], 0, v[156:157]
	s_waitcnt lgkmcnt(0)
	v_pk_mul_f32 v[40:41], v[174:175], v[36:37] op_sel_hi:[1,0]
	v_pk_mul_f32 v[30:31], v[30:31], v[36:37] op_sel_hi:[1,0]
	v_pk_mul_f32 v[24:25], v[24:25], v[36:37] op_sel_hi:[1,0]
	v_pk_mul_f32 v[20:21], v[20:21], v[36:37] op_sel_hi:[1,0]
	v_pk_mul_f32 v[16:17], v[16:17], v[36:37] op_sel_hi:[1,0]
	v_pk_mul_f32 v[34:35], v[226:227], v[30:31]
	v_pk_mul_f32 v[32:33], v[224:225], v[40:41]
	global_store_dwordx4 v[38:39], v[32:35], off
	s_nop 1
	s_nop 0
	v_pk_mul_f32 v[34:35], v[26:27], v[36:37] op_sel_hi:[1,0]
	v_pk_mul_f32 v[26:27], v[24:25], v[230:231]
	v_pk_mul_f32 v[24:25], v[34:35], v[228:229]
	global_store_dwordx4 v[38:39], v[24:27], off offset:64
	v_pk_mul_f32 v[30:31], v[22:23], v[36:37] op_sel_hi:[1,0]
	v_pk_mul_f32 v[22:23], v[20:21], v[234:235]
	v_pk_mul_f32 v[20:21], v[30:31], v[232:233]
	global_store_dwordx4 v[38:39], v[20:23], off offset:512
	v_pk_mul_f32 v[24:25], v[18:19], v[36:37] op_sel_hi:[1,0]
	v_pk_mul_f32 v[18:19], v[16:17], v[238:239]
	v_pk_mul_f32 v[16:17], v[24:25], v[236:237]
	global_store_dwordx4 v[38:39], v[16:19], off offset:576
	v_lshlrev_b64 v[20:21], 11, v[28:29]
	v_mov_b32_e32 v22, v37
	v_lshl_add_u64 v[20:21], v[20:21], 2, s[60:61]
	v_pk_mul_f32 v[24:25], v[14:15], v[22:23] op_sel_hi:[1,0]
	v_pk_mul_f32 v[12:13], v[12:13], v[22:23] op_sel_hi:[1,0]
	v_lshl_add_u64 v[20:21], v[20:21], 0, v[156:157]
	v_pk_mul_f32 v[8:9], v[8:9], v[22:23] op_sel_hi:[1,0]
	v_pk_mul_f32 v[4:5], v[4:5], v[22:23] op_sel_hi:[1,0]
	v_pk_mul_f32 v[0:1], v[0:1], v[22:23] op_sel_hi:[1,0]
	v_pk_mul_f32 v[14:15], v[226:227], v[12:13]
	v_pk_mul_f32 v[12:13], v[224:225], v[24:25]
	global_store_dwordx4 v[20:21], v[12:15], off
	v_pk_mul_f32 v[16:17], v[10:11], v[22:23] op_sel_hi:[1,0]
	v_pk_mul_f32 v[10:11], v[8:9], v[230:231]
	v_pk_mul_f32 v[8:9], v[16:17], v[228:229]
	global_store_dwordx4 v[20:21], v[8:11], off offset:64
	v_pk_mul_f32 v[12:13], v[6:7], v[22:23] op_sel_hi:[1,0]
	v_pk_mul_f32 v[6:7], v[4:5], v[234:235]
	v_pk_mul_f32 v[4:5], v[12:13], v[232:233]
	global_store_dwordx4 v[20:21], v[4:7], off offset:512
	v_pk_mul_f32 v[8:9], v[2:3], v[22:23] op_sel_hi:[1,0]
	v_pk_mul_f32 v[2:3], v[0:1], v[238:239]
	v_pk_mul_f32 v[0:1], v[8:9], v[236:237]
	global_store_dwordx4 v[20:21], v[0:3], off offset:576
	s_cbranch_scc1 .LBB0_527
	s_andn2_b64 vcc, exec, s[8:9]
	s_cbranch_vccnz .LBB0_526
	s_barrier
	s_branch .LBB0_526
